# GOUT residual epilogue: the read-once x_in tile loaded non-temporally (nt) so the freshly written x_out keeps its place in L2/MALL for the following NORM phase
# baseline (speedup 1.0000x reference)
; #define GM_WAIT_V(n) asm volatile("s_waitcnt vmcnt(" #n ")" ::: "memory")
; #define GM_WAIT_L(n) asm volatile("s_waitcnt lgkmcnt(" #n ")" ::: "memory")
; #define GM_BAR __builtin_amdgcn_s_barrier()
; #define GM_SCHED __builtin_amdgcn_sched_barrier(0)
; #define GM_LDA(dst, b, h) _Pragma("unroll") for (int m = 0; m < 4; ++m) _Pragma("unroll") for (int k = 0; k < 2; ++k) \
;         dst[m][k] = *(const LAS bf16x8*)(GM_SA(b, h) + aoff + (m * 2 + k) * 1024)
; #define GM_LDB(dst, b, h) _Pragma("unroll") for (int n = 0; n < 2; ++n) _Pragma("unroll") for (int k = 0; k < 2; ++k) \
;         dst[n][k] = *(const LAS bf16x8*)(GM_SB(b, h) + boff + (n * 2 + k) * 1024)
; template <class Epi>
; __device__ __forceinline__ void gemm_phase(const bf16_t* __restrict__ A, const bf16_t* __restrict__ Bt, int M, int N, LAS unsigned char* lds, const Epi& epi, int vcu) {
;     ...
;         for (int t = 0; t < NT; t += 2) {
;             const bool lastk = (t + 2 >= NT);
;             const int prow = lastk ? nrow : brow, pcol = lastk ? ncol : bcol, k2 = lastk ? 0 : t + 2, k3 = lastk ? 1 : t + 3;
;             GM_LDB(B0, 0, 0); GM_SCHED; GM_LDA(At, 0, 0); GM_STAGE(GM_SA(1, 1), A, brow + HALF, t + 1);
;             GM_WAIT_L(8); GM_BAR; GM_WAIT_L(0); GM_MMA(0, 0, At, B0); GM_BAR; GM_SCHED;
;             GM_LDB(B1, 0, 1); GM_STAGE(GM_SB(0, 0), Bt, pcol, k2);
;             GM_BAR; GM_WAIT_L(0); GM_MMA(0, 1, At, B1); GM_BAR;
;             GM_LDA(At, 0, 1); GM_STAGE(GM_SA(0, 0), A, prow, k2);
;             GM_BAR; GM_WAIT_L(0); GM_MMA(1, 0, At, B0); GM_BAR; GM_SCHED;
;             GM_STAGE(GM_SB(0, 1), Bt, pcol + HALF, k2);
;             GM_WAIT_V(6); GM_BAR; GM_MMA(1, 1, At, B1); GM_BAR;
;             GM_LDB(B0, 1, 0); GM_SCHED; GM_LDA(At, 1, 0); GM_STAGE(GM_SA(0, 1), A, prow + HALF, k2);
;             GM_WAIT_L(8); GM_BAR; GM_WAIT_L(0); GM_MMA(0, 0, At, B0); GM_BAR; GM_SCHED;
;             GM_LDB(B1, 1, 1); GM_STAGE(GM_SB(1, 0), Bt, pcol, k3);
;             GM_BAR; GM_WAIT_L(0); GM_MMA(0, 1, At, B1); GM_BAR;
;             GM_LDA(At, 1, 1); GM_STAGE(GM_SA(1, 0), A, prow, k3);
;             GM_BAR; GM_WAIT_L(0); GM_MMA(1, 0, At, B0); GM_BAR; GM_SCHED;
;             GM_STAGE(GM_SB(1, 1), Bt, pcol + HALF, k3);
;             GM_WAIT_V(6); GM_BAR; GM_MMA(1, 1, At, B1); GM_BAR;
.LBB0_339:
	s_add_i32 s37, s37, 2
	v_add_u32_e32 v149, s88, v147
	s_cmp_gt_u32 s37, 13
	ds_read_b128 v[150:153], v149
	ds_read_b128 v[154:157], v149 offset:1024
	ds_read_b128 v[158:161], v149 offset:2048
	ds_read_b128 v[162:165], v149 offset:3072
	s_cselect_b64 s[48:49], -1, 0
	s_and_b64 s[48:49], s[48:49], exec
	s_cselect_b32 s48, 64, s43
	s_sub_i32 s10, s43, 64
	s_cmp_gt_u32 s37, 13
	s_cselect_b64 s[52:53], -1, 0
	s_and_b64 vcc, s[52:53], exec
	s_cselect_b32 s54, s29, s42
	s_cselect_b32 s52, s28, s44
	s_cselect_b32 s96, 0, s10
	v_add_u32_e32 v199, 0xc000, v133
	v_mov_b32_e32 v149, v130
	v_mov_b32_e32 v198, v1
	v_readfirstlane_b32 s10, v199
	ds_read_b128 v[166:169], v148
	ds_read_b128 v[170:173], v148 offset:1024
	ds_read_b128 v[174:177], v148 offset:2048
	ds_read_b128 v[178:181], v148 offset:3072
	ds_read_b128 v[182:185], v148 offset:4096
	ds_read_b128 v[186:189], v148 offset:5120
	ds_read_b128 v[190:193], v148 offset:6144
	ds_read_b128 v[194:197], v148 offset:7168
	s_mov_b32 m0, s10
	s_nop 0
	global_load_lds_dwordx4 v198, s[46:47]
	v_add_u32_e32 v198, 0xe000, v133
	s_nop 0
	v_readfirstlane_b32 s10, v198
	s_mov_b32 m0, s10
	s_nop 0
	global_load_lds_dwordx4 v149, s[46:47]
	s_waitcnt lgkmcnt(8)
	s_barrier
	s_waitcnt lgkmcnt(0)
	s_setprio 1
	s_waitcnt lgkmcnt(0)
	v_mfma_f32_16x16x32_bf16 v[126:129], v[150:153], v[166:169], v[126:129]
	v_mfma_f32_16x16x32_bf16 v[122:125], v[158:161], v[166:169], v[122:125]
	v_mfma_f32_16x16x32_bf16 v[110:113], v[150:153], v[174:177], v[110:113]
	v_mfma_f32_16x16x32_bf16 v[106:109], v[158:161], v[174:177], v[106:109]
	v_mfma_f32_16x16x32_bf16 v[94:97], v[150:153], v[182:185], v[94:97]
	v_mfma_f32_16x16x32_bf16 v[90:93], v[158:161], v[182:185], v[90:93]
	v_mfma_f32_16x16x32_bf16 v[78:81], v[150:153], v[190:193], v[78:81]
	v_mfma_f32_16x16x32_bf16 v[74:77], v[158:161], v[190:193], v[74:77]
	v_mfma_f32_16x16x32_bf16 v[126:129], v[154:157], v[170:173], v[126:129]
	v_mfma_f32_16x16x32_bf16 v[122:125], v[162:165], v[170:173], v[122:125]
	v_mfma_f32_16x16x32_bf16 v[110:113], v[154:157], v[178:181], v[110:113]
	v_mfma_f32_16x16x32_bf16 v[106:109], v[162:165], v[178:181], v[106:109]
	v_mfma_f32_16x16x32_bf16 v[94:97], v[154:157], v[186:189], v[94:97]
	v_mfma_f32_16x16x32_bf16 v[90:93], v[162:165], v[186:189], v[90:93]
	v_mfma_f32_16x16x32_bf16 v[78:81], v[154:157], v[194:197], v[78:81]
	v_mfma_f32_16x16x32_bf16 v[74:77], v[162:165], v[194:197], v[74:77]
	s_setprio 0
	s_barrier
	s_ashr_i32 s53, s52, 31
	s_lshl_b64 s[56:57], s[52:53], 11
	s_add_u32 s10, s25, s56
	s_addc_u32 s11, s34, s57
	s_lshl_b64 s[56:57], s[96:97], 1
	v_add_u32_e32 v149, s89, v147
	s_add_u32 s64, s10, s56
	v_readfirstlane_b32 s45, v131
	ds_read_b128 v[198:201], v149
	ds_read_b128 v[202:205], v149 offset:1024
	ds_read_b128 v[212:215], v149 offset:2048
	ds_read_b128 v[216:219], v149 offset:3072
	s_addc_u32 s65, s11, s57
	v_mov_b32_e32 v149, v130
	v_mov_b32_e32 v208, v1
	s_mov_b32 m0, s45
	v_readfirstlane_b32 s45, v132
	s_nop 0
	global_load_lds_dwordx4 v208, s[64:65]
	s_mov_b32 m0, s45
	s_nop 0
	global_load_lds_dwordx4 v149, s[64:65]
	s_barrier
	s_waitcnt lgkmcnt(0)
	s_setprio 1
	s_waitcnt lgkmcnt(0)
	v_mfma_f32_16x16x32_bf16 v[118:121], v[198:201], v[166:169], v[118:121]
	v_mfma_f32_16x16x32_bf16 v[114:117], v[212:215], v[166:169], v[114:117]
	v_mfma_f32_16x16x32_bf16 v[102:105], v[198:201], v[174:177], v[102:105]
	v_mfma_f32_16x16x32_bf16 v[98:101], v[212:215], v[174:177], v[98:101]
	v_mfma_f32_16x16x32_bf16 v[86:89], v[198:201], v[182:185], v[86:89]
	v_mfma_f32_16x16x32_bf16 v[82:85], v[212:215], v[182:185], v[82:85]
	v_mfma_f32_16x16x32_bf16 v[70:73], v[198:201], v[190:193], v[70:73]
	v_mfma_f32_16x16x32_bf16 v[66:69], v[212:215], v[190:193], v[66:69]
	v_mfma_f32_16x16x32_bf16 v[118:121], v[202:205], v[170:173], v[118:121]
	v_mfma_f32_16x16x32_bf16 v[114:117], v[216:219], v[170:173], v[114:117]
	v_mfma_f32_16x16x32_bf16 v[102:105], v[202:205], v[178:181], v[102:105]
	v_mfma_f32_16x16x32_bf16 v[98:101], v[216:219], v[178:181], v[98:101]
	v_mfma_f32_16x16x32_bf16 v[86:89], v[202:205], v[186:189], v[86:89]
	v_mfma_f32_16x16x32_bf16 v[82:85], v[216:219], v[186:189], v[82:85]
	v_mfma_f32_16x16x32_bf16 v[70:73], v[202:205], v[194:197], v[70:73]
	v_mfma_f32_16x16x32_bf16 v[66:69], v[216:219], v[194:197], v[66:69]
	s_setprio 0
	s_ashr_i32 s55, s54, 31
	s_lshl_b64 s[54:55], s[54:55], 11
	s_add_u32 s45, s74, s54
	s_addc_u32 s51, s75, s55
	s_add_u32 s54, s45, s56
	v_readfirstlane_b32 s49, v133
	s_addc_u32 s55, s51, s57
	v_mov_b32_e32 v149, v130
	v_mov_b32_e32 v208, v1
	s_mov_b32 m0, s49
	v_readfirstlane_b32 s49, v134
	s_barrier
	ds_read_b128 v[166:169], v148 offset:16384
	ds_read_b128 v[170:173], v148 offset:17408
	ds_read_b128 v[174:177], v148 offset:18432
	ds_read_b128 v[178:181], v148 offset:19456
	ds_read_b128 v[182:185], v148 offset:20480
	ds_read_b128 v[186:189], v148 offset:21504
	ds_read_b128 v[190:193], v148 offset:22528
	ds_read_b128 v[194:197], v148 offset:23552
	s_nop 0
	global_load_lds_dwordx4 v208, s[54:55]
	s_mov_b32 m0, s49
	s_nop 0
	global_load_lds_dwordx4 v149, s[54:55]
	s_barrier
; #define GM_WAIT_V(n) asm volatile("s_waitcnt vmcnt(" #n ")" ::: "memory")
; #define GM_WAIT_L(n) asm volatile("s_waitcnt lgkmcnt(" #n ")" ::: "memory")
; #define GM_BAR __builtin_amdgcn_s_barrier()
; #define GM_SCHED __builtin_amdgcn_sched_barrier(0)
; #define GM_LDA(dst, b, h) _Pragma("unroll") for (int m = 0; m < 4; ++m) _Pragma("unroll") for (int k = 0; k < 2; ++k) \
;         dst[m][k] = *(const LAS bf16x8*)(GM_SA(b, h) + aoff + (m * 2 + k) * 1024)
; #define GM_LDB(dst, b, h) _Pragma("unroll") for (int n = 0; n < 2; ++n) _Pragma("unroll") for (int k = 0; k < 2; ++k) \
;         dst[n][k] = *(const LAS bf16x8*)(GM_SB(b, h) + boff + (n * 2 + k) * 1024)
; template <class Epi>
; __device__ __forceinline__ void gemm_phase(const bf16_t* __restrict__ A, const bf16_t* __restrict__ Bt, int M, int N, LAS unsigned char* lds, const Epi& epi, int vcu) {
;     ...
;         for (int t = 0; t < NT; t += 2) {
;             const bool lastk = (t + 2 >= NT);
;             const int prow = lastk ? nrow : brow, pcol = lastk ? ncol : bcol, k2 = lastk ? 0 : t + 2, k3 = lastk ? 1 : t + 3;
;             GM_LDB(B0, 0, 0); GM_SCHED; GM_LDA(At, 0, 0); GM_STAGE(GM_SA(1, 1), A, brow + HALF, t + 1);
;             GM_WAIT_L(8); GM_BAR; GM_WAIT_L(0); GM_MMA(0, 0, At, B0); GM_BAR; GM_SCHED;
;             GM_LDB(B1, 0, 1); GM_STAGE(GM_SB(0, 0), Bt, pcol, k2);
;             GM_BAR; GM_WAIT_L(0); GM_MMA(0, 1, At, B1); GM_BAR;
;             GM_LDA(At, 0, 1); GM_STAGE(GM_SA(0, 0), A, prow, k2);
;             GM_BAR; GM_WAIT_L(0); GM_MMA(1, 0, At, B0); GM_BAR; GM_SCHED;
;             GM_STAGE(GM_SB(0, 1), Bt, pcol + HALF, k2);
;             GM_WAIT_V(6); GM_BAR; GM_MMA(1, 1, At, B1); GM_BAR;
;             GM_LDB(B0, 1, 0); GM_SCHED; GM_LDA(At, 1, 0); GM_STAGE(GM_SA(0, 1), A, prow + HALF, k2);
;             GM_WAIT_L(8); GM_BAR; GM_WAIT_L(0); GM_MMA(0, 0, At, B0); GM_BAR; GM_SCHED;
;             GM_LDB(B1, 1, 1); GM_STAGE(GM_SB(1, 0), Bt, pcol, k3);
;             GM_BAR; GM_WAIT_L(0); GM_MMA(0, 1, At, B1); GM_BAR;
;             GM_LDA(At, 1, 1); GM_STAGE(GM_SA(1, 0), A, prow, k3);
;             GM_BAR; GM_WAIT_L(0); GM_MMA(1, 0, At, B0); GM_BAR; GM_SCHED;
;             GM_STAGE(GM_SB(1, 1), Bt, pcol + HALF, k3);
;             GM_WAIT_V(6); GM_BAR; GM_MMA(1, 1, At, B1); GM_BAR;
	s_waitcnt lgkmcnt(0)
	s_setprio 1
	s_waitcnt lgkmcnt(0)
	v_mfma_f32_16x16x32_bf16 v[62:65], v[150:153], v[166:169], v[62:65]
	v_mfma_f32_16x16x32_bf16 v[58:61], v[158:161], v[166:169], v[58:61]
	v_mfma_f32_16x16x32_bf16 v[46:49], v[150:153], v[174:177], v[46:49]
	v_mfma_f32_16x16x32_bf16 v[42:45], v[158:161], v[174:177], v[42:45]
	v_mfma_f32_16x16x32_bf16 v[30:33], v[150:153], v[182:185], v[30:33]
	v_mfma_f32_16x16x32_bf16 v[26:29], v[158:161], v[182:185], v[26:29]
	v_mfma_f32_16x16x32_bf16 v[14:17], v[150:153], v[190:193], v[14:17]
	v_mfma_f32_16x16x32_bf16 v[10:13], v[158:161], v[190:193], v[10:13]
	v_mfma_f32_16x16x32_bf16 v[62:65], v[154:157], v[170:173], v[62:65]
	v_mfma_f32_16x16x32_bf16 v[58:61], v[162:165], v[170:173], v[58:61]
	v_mfma_f32_16x16x32_bf16 v[46:49], v[154:157], v[178:181], v[46:49]
	v_mfma_f32_16x16x32_bf16 v[42:45], v[162:165], v[178:181], v[42:45]
	v_mfma_f32_16x16x32_bf16 v[30:33], v[154:157], v[186:189], v[30:33]
	v_mfma_f32_16x16x32_bf16 v[26:29], v[162:165], v[186:189], v[26:29]
	v_mfma_f32_16x16x32_bf16 v[14:17], v[154:157], v[194:197], v[14:17]
	v_mfma_f32_16x16x32_bf16 v[10:13], v[162:165], v[194:197], v[10:13]
	s_setprio 0
	s_barrier
	s_bitset1_b32 s52, 7
	s_ashr_i32 s53, s52, 31
	s_lshl_b64 s[52:53], s[52:53], 11
	s_add_u32 s58, s25, s52
	s_addc_u32 s59, s34, s53
	s_add_u32 s52, s58, s56
	v_readfirstlane_b32 s49, v135
	s_addc_u32 s53, s59, s57
	v_mov_b32_e32 v149, v130
	v_mov_b32_e32 v150, v1
	s_mov_b32 m0, s49
	v_readfirstlane_b32 s49, v136
	s_nop 0
	global_load_lds_dwordx4 v150, s[52:53]
	s_mov_b32 m0, s49
	s_nop 0
	global_load_lds_dwordx4 v149, s[52:53]
	s_waitcnt vmcnt(6)
	s_barrier
	s_setprio 1
	v_mfma_f32_16x16x32_bf16 v[54:57], v[198:201], v[166:169], v[54:57]
	v_mfma_f32_16x16x32_bf16 v[50:53], v[212:215], v[166:169], v[50:53]
	v_mfma_f32_16x16x32_bf16 v[38:41], v[198:201], v[174:177], v[38:41]
	v_mfma_f32_16x16x32_bf16 v[34:37], v[212:215], v[174:177], v[34:37]
	v_mfma_f32_16x16x32_bf16 v[22:25], v[198:201], v[182:185], v[22:25]
	v_mfma_f32_16x16x32_bf16 v[18:21], v[212:215], v[182:185], v[18:21]
	v_mfma_f32_16x16x32_bf16 v[6:9], v[198:201], v[190:193], v[6:9]
	v_mfma_f32_16x16x32_bf16 v[2:5], v[212:215], v[190:193], v[2:5]
	v_mfma_f32_16x16x32_bf16 v[54:57], v[202:205], v[170:173], v[54:57]
	v_mfma_f32_16x16x32_bf16 v[50:53], v[216:219], v[170:173], v[50:53]
	v_mfma_f32_16x16x32_bf16 v[38:41], v[202:205], v[178:181], v[38:41]
	v_mfma_f32_16x16x32_bf16 v[34:37], v[216:219], v[178:181], v[34:37]
	v_mfma_f32_16x16x32_bf16 v[22:25], v[202:205], v[186:189], v[22:25]
	v_mfma_f32_16x16x32_bf16 v[18:21], v[216:219], v[186:189], v[18:21]
	v_mfma_f32_16x16x32_bf16 v[6:9], v[202:205], v[194:197], v[6:9]
	v_mfma_f32_16x16x32_bf16 v[2:5], v[216:219], v[194:197], v[2:5]
	s_setprio 0
	v_add_u32_e32 v149, s16, v147
	s_barrier
	ds_read_b128 v[150:153], v149
	ds_read_b128 v[154:157], v149 offset:1024
	ds_read_b128 v[158:161], v149 offset:2048
	ds_read_b128 v[162:165], v149 offset:3072
	s_add_u32 s52, s54, 0x40000
	v_readfirstlane_b32 s49, v137
	s_addc_u32 s53, s55, 0
	v_mov_b32_e32 v149, v130
	v_mov_b32_e32 v198, v1
	s_mov_b32 m0, s49
	v_readfirstlane_b32 s49, v138
	ds_read_b128 v[166:169], v148 offset:32768
	ds_read_b128 v[170:173], v148 offset:33792
	ds_read_b128 v[174:177], v148 offset:34816
	ds_read_b128 v[178:181], v148 offset:35840
	ds_read_b128 v[182:185], v148 offset:36864
	ds_read_b128 v[186:189], v148 offset:37888
	ds_read_b128 v[190:193], v148 offset:38912
	ds_read_b128 v[194:197], v148 offset:39936
	s_nop 0
	global_load_lds_dwordx4 v198, s[52:53]
	s_mov_b32 m0, s49
	s_nop 0
	global_load_lds_dwordx4 v149, s[52:53]
	s_waitcnt lgkmcnt(8)
	s_barrier
	s_waitcnt lgkmcnt(0)
	s_setprio 1
	s_waitcnt lgkmcnt(0)
	v_mfma_f32_16x16x32_bf16 v[126:129], v[150:153], v[166:169], v[126:129]
	v_mfma_f32_16x16x32_bf16 v[122:125], v[158:161], v[166:169], v[122:125]
	v_mfma_f32_16x16x32_bf16 v[110:113], v[150:153], v[174:177], v[110:113]
	v_mfma_f32_16x16x32_bf16 v[106:109], v[158:161], v[174:177], v[106:109]
	v_mfma_f32_16x16x32_bf16 v[94:97], v[150:153], v[182:185], v[94:97]
	v_mfma_f32_16x16x32_bf16 v[90:93], v[158:161], v[182:185], v[90:93]
	v_mfma_f32_16x16x32_bf16 v[78:81], v[150:153], v[190:193], v[78:81]
	v_mfma_f32_16x16x32_bf16 v[74:77], v[158:161], v[190:193], v[74:77]
	v_mfma_f32_16x16x32_bf16 v[126:129], v[154:157], v[170:173], v[126:129]
	v_mfma_f32_16x16x32_bf16 v[122:125], v[162:165], v[170:173], v[122:125]
	v_mfma_f32_16x16x32_bf16 v[110:113], v[154:157], v[178:181], v[110:113]
	v_mfma_f32_16x16x32_bf16 v[106:109], v[162:165], v[178:181], v[106:109]
	v_mfma_f32_16x16x32_bf16 v[94:97], v[154:157], v[186:189], v[94:97]
	v_mfma_f32_16x16x32_bf16 v[90:93], v[162:165], v[186:189], v[90:93]
	v_mfma_f32_16x16x32_bf16 v[78:81], v[154:157], v[194:197], v[78:81]
	v_mfma_f32_16x16x32_bf16 v[74:77], v[162:165], v[194:197], v[74:77]
	s_setprio 0
	s_barrier
	s_mov_b32 s49, s97
	s_lshl_b64 s[48:49], s[48:49], 1
	v_add_u32_e32 v149, s17, v147
	s_add_u32 s52, s10, s48
	v_readfirstlane_b32 s10, v139
	ds_read_b128 v[198:201], v149
	ds_read_b128 v[202:205], v149 offset:1024
	ds_read_b128 v[212:215], v149 offset:2048
	ds_read_b128 v[216:219], v149 offset:3072
	s_addc_u32 s53, s11, s49
	v_mov_b32_e32 v149, v130
	v_mov_b32_e32 v208, v1
	s_mov_b32 m0, s10
	v_readfirstlane_b32 s10, v140
	s_nop 0
	global_load_lds_dwordx4 v208, s[52:53]
	s_mov_b32 m0, s10
	s_nop 0
	global_load_lds_dwordx4 v149, s[52:53]
	s_barrier
; #define GM_WAIT_V(n) asm volatile("s_waitcnt vmcnt(" #n ")" ::: "memory")
; #define GM_WAIT_L(n) asm volatile("s_waitcnt lgkmcnt(" #n ")" ::: "memory")
; #define GM_BAR __builtin_amdgcn_s_barrier()
; #define GM_SCHED __builtin_amdgcn_sched_barrier(0)
; #define GM_LDA(dst, b, h) _Pragma("unroll") for (int m = 0; m < 4; ++m) _Pragma("unroll") for (int k = 0; k < 2; ++k) \
;         dst[m][k] = *(const LAS bf16x8*)(GM_SA(b, h) + aoff + (m * 2 + k) * 1024)
; #define GM_LDB(dst, b, h) _Pragma("unroll") for (int n = 0; n < 2; ++n) _Pragma("unroll") for (int k = 0; k < 2; ++k) \
;         dst[n][k] = *(const LAS bf16x8*)(GM_SB(b, h) + boff + (n * 2 + k) * 1024)
; template <class Epi>
; __device__ __forceinline__ void gemm_phase(const bf16_t* __restrict__ A, const bf16_t* __restrict__ Bt, int M, int N, LAS unsigned char* lds, const Epi& epi, int vcu) {
;     ...
;         for (int t = 0; t < NT; t += 2) {
;             const bool lastk = (t + 2 >= NT);
;             const int prow = lastk ? nrow : brow, pcol = lastk ? ncol : bcol, k2 = lastk ? 0 : t + 2, k3 = lastk ? 1 : t + 3;
;             GM_LDB(B0, 0, 0); GM_SCHED; GM_LDA(At, 0, 0); GM_STAGE(GM_SA(1, 1), A, brow + HALF, t + 1);
;             GM_WAIT_L(8); GM_BAR; GM_WAIT_L(0); GM_MMA(0, 0, At, B0); GM_BAR; GM_SCHED;
;             GM_LDB(B1, 0, 1); GM_STAGE(GM_SB(0, 0), Bt, pcol, k2);
;             GM_BAR; GM_WAIT_L(0); GM_MMA(0, 1, At, B1); GM_BAR;
;             GM_LDA(At, 0, 1); GM_STAGE(GM_SA(0, 0), A, prow, k2);
;             GM_BAR; GM_WAIT_L(0); GM_MMA(1, 0, At, B0); GM_BAR; GM_SCHED;
;             GM_STAGE(GM_SB(0, 1), Bt, pcol + HALF, k2);
;             GM_WAIT_V(6); GM_BAR; GM_MMA(1, 1, At, B1); GM_BAR;
;             GM_LDB(B0, 1, 0); GM_SCHED; GM_LDA(At, 1, 0); GM_STAGE(GM_SA(0, 1), A, prow + HALF, k2);
;             GM_WAIT_L(8); GM_BAR; GM_WAIT_L(0); GM_MMA(0, 0, At, B0); GM_BAR; GM_SCHED;
;             GM_LDB(B1, 1, 1); GM_STAGE(GM_SB(1, 0), Bt, pcol, k3);
;             GM_BAR; GM_WAIT_L(0); GM_MMA(0, 1, At, B1); GM_BAR;
;             GM_LDA(At, 1, 1); GM_STAGE(GM_SA(1, 0), A, prow, k3);
;             GM_BAR; GM_WAIT_L(0); GM_MMA(1, 0, At, B0); GM_BAR; GM_SCHED;
;             GM_STAGE(GM_SB(1, 1), Bt, pcol + HALF, k3);
;             GM_WAIT_V(6); GM_BAR; GM_MMA(1, 1, At, B1); GM_BAR;
;         }
	s_waitcnt lgkmcnt(0)
	s_setprio 1
	s_waitcnt lgkmcnt(0)
	v_mfma_f32_16x16x32_bf16 v[118:121], v[198:201], v[166:169], v[118:121]
	v_mfma_f32_16x16x32_bf16 v[114:117], v[212:215], v[166:169], v[114:117]
	v_mfma_f32_16x16x32_bf16 v[102:105], v[198:201], v[174:177], v[102:105]
	v_mfma_f32_16x16x32_bf16 v[98:101], v[212:215], v[174:177], v[98:101]
	v_mfma_f32_16x16x32_bf16 v[86:89], v[198:201], v[182:185], v[86:89]
	v_mfma_f32_16x16x32_bf16 v[82:85], v[212:215], v[182:185], v[82:85]
	v_mfma_f32_16x16x32_bf16 v[70:73], v[198:201], v[190:193], v[70:73]
	v_mfma_f32_16x16x32_bf16 v[66:69], v[212:215], v[190:193], v[66:69]
	v_mfma_f32_16x16x32_bf16 v[118:121], v[202:205], v[170:173], v[118:121]
	v_mfma_f32_16x16x32_bf16 v[114:117], v[216:219], v[170:173], v[114:117]
	v_mfma_f32_16x16x32_bf16 v[102:105], v[202:205], v[178:181], v[102:105]
	v_mfma_f32_16x16x32_bf16 v[98:101], v[216:219], v[178:181], v[98:101]
	v_mfma_f32_16x16x32_bf16 v[86:89], v[202:205], v[186:189], v[86:89]
	v_mfma_f32_16x16x32_bf16 v[82:85], v[216:219], v[186:189], v[82:85]
	v_mfma_f32_16x16x32_bf16 v[70:73], v[202:205], v[194:197], v[70:73]
	v_mfma_f32_16x16x32_bf16 v[66:69], v[216:219], v[194:197], v[66:69]
	s_setprio 0
	s_add_u32 s52, s45, s48
	v_readfirstlane_b32 s10, v141
	s_addc_u32 s53, s51, s49
	v_mov_b32_e32 v149, v130
	v_mov_b32_e32 v208, v1
	s_mov_b32 m0, s10
	v_readfirstlane_b32 s10, v142
	s_barrier
	ds_read_b128 v[166:169], v148 offset:49152
	ds_read_b128 v[170:173], v148 offset:50176
	ds_read_b128 v[174:177], v148 offset:51200
	ds_read_b128 v[178:181], v148 offset:52224
	ds_read_b128 v[182:185], v148 offset:53248
	ds_read_b128 v[186:189], v148 offset:54272
	ds_read_b128 v[190:193], v148 offset:55296
	ds_read_b128 v[194:197], v148 offset:56320
	s_nop 0
	global_load_lds_dwordx4 v208, s[52:53]
	s_mov_b32 m0, s10
	s_nop 0
	global_load_lds_dwordx4 v149, s[52:53]
	s_barrier
	s_waitcnt lgkmcnt(0)
	s_setprio 1
	s_waitcnt lgkmcnt(0)
	v_mfma_f32_16x16x32_bf16 v[62:65], v[150:153], v[166:169], v[62:65]
	v_mfma_f32_16x16x32_bf16 v[58:61], v[158:161], v[166:169], v[58:61]
	v_mfma_f32_16x16x32_bf16 v[46:49], v[150:153], v[174:177], v[46:49]
	v_mfma_f32_16x16x32_bf16 v[42:45], v[158:161], v[174:177], v[42:45]
	v_mfma_f32_16x16x32_bf16 v[30:33], v[150:153], v[182:185], v[30:33]
	v_mfma_f32_16x16x32_bf16 v[26:29], v[158:161], v[182:185], v[26:29]
	v_mfma_f32_16x16x32_bf16 v[14:17], v[150:153], v[190:193], v[14:17]
	v_mfma_f32_16x16x32_bf16 v[10:13], v[158:161], v[190:193], v[10:13]
	v_mfma_f32_16x16x32_bf16 v[62:65], v[154:157], v[170:173], v[62:65]
	v_mfma_f32_16x16x32_bf16 v[58:61], v[162:165], v[170:173], v[58:61]
	v_mfma_f32_16x16x32_bf16 v[46:49], v[154:157], v[178:181], v[46:49]
	v_mfma_f32_16x16x32_bf16 v[42:45], v[162:165], v[178:181], v[42:45]
	v_mfma_f32_16x16x32_bf16 v[30:33], v[154:157], v[186:189], v[30:33]
	v_mfma_f32_16x16x32_bf16 v[26:29], v[162:165], v[186:189], v[26:29]
	v_mfma_f32_16x16x32_bf16 v[14:17], v[154:157], v[194:197], v[14:17]
	v_mfma_f32_16x16x32_bf16 v[10:13], v[162:165], v[194:197], v[10:13]
	s_setprio 0
	s_barrier
	s_add_u32 s48, s58, s48
	v_readfirstlane_b32 s10, v143
	s_addc_u32 s49, s59, s49
	v_mov_b32_e32 v149, v130
	v_mov_b32_e32 v150, v1
	s_mov_b32 m0, s10
	v_readfirstlane_b32 s10, v144
	s_nop 0
	global_load_lds_dwordx4 v150, s[48:49]
	s_mov_b32 m0, s10
	s_nop 0
	global_load_lds_dwordx4 v149, s[48:49]
	s_waitcnt vmcnt(6)
	s_barrier
	s_setprio 1
	v_mfma_f32_16x16x32_bf16 v[54:57], v[198:201], v[166:169], v[54:57]
	v_mfma_f32_16x16x32_bf16 v[50:53], v[212:215], v[166:169], v[50:53]
	v_mfma_f32_16x16x32_bf16 v[38:41], v[198:201], v[174:177], v[38:41]
	v_mfma_f32_16x16x32_bf16 v[34:37], v[212:215], v[174:177], v[34:37]
	v_mfma_f32_16x16x32_bf16 v[22:25], v[198:201], v[182:185], v[22:25]
	v_mfma_f32_16x16x32_bf16 v[18:21], v[212:215], v[182:185], v[18:21]
	v_mfma_f32_16x16x32_bf16 v[6:9], v[198:201], v[190:193], v[6:9]
	v_mfma_f32_16x16x32_bf16 v[2:5], v[212:215], v[190:193], v[2:5]
	v_mfma_f32_16x16x32_bf16 v[54:57], v[202:205], v[170:173], v[54:57]
	v_mfma_f32_16x16x32_bf16 v[50:53], v[216:219], v[170:173], v[50:53]
	v_mfma_f32_16x16x32_bf16 v[38:41], v[202:205], v[178:181], v[38:41]
	v_mfma_f32_16x16x32_bf16 v[34:37], v[216:219], v[178:181], v[34:37]
	v_mfma_f32_16x16x32_bf16 v[22:25], v[202:205], v[186:189], v[22:25]
	v_mfma_f32_16x16x32_bf16 v[18:21], v[216:219], v[186:189], v[18:21]
	v_mfma_f32_16x16x32_bf16 v[6:9], v[202:205], v[194:197], v[6:9]
	v_mfma_f32_16x16x32_bf16 v[2:5], v[216:219], v[194:197], v[2:5]
	s_setprio 0
	s_addk_i32 s43, 0x80
	s_add_u32 s46, s46, 0x100
	s_addc_u32 s47, s47, 0
	s_barrier
	s_cbranch_vccz .LBB0_339
; template <class Epi>
; __device__ __forceinline__ void gemm_phase(const bf16_t* __restrict__ A, const bf16_t* __restrict__ Bt, int M, int N, LAS unsigned char* lds, const Epi& epi, int vcu) {
;     ...
;         for (int ai = 0; ai < 2; ++ai)
; #pragma unroll
;             for (int mp = 0; mp < 2; ++mp) {
; #pragma unroll
;                 for (int mq = 0; mq < 2; ++mq)
; #pragma unroll
;                     for (int bj = 0; bj < 2; ++bj) { const int m = mp * 2 + mq;
;                         epi(brow + ai * HALF + wr * 64 + m * 16 + fre, (bcol + bj * HALF + wc * 32) >> 5, fqe, acc[ai][bj][m][0], acc[ai][bj][m][1]); }
	s_add_i32 s10, s42, s4
	v_add_u32_e32 v149, s10, v145
	s_or_b32 s11, s44, s5
	v_lshl_add_u32 v212, v146, 3, s11
	s_lshr_b32 s2, s42, 13
	s_mul_i32 s2, s2, 0x3000
	s_add_u32 s10, s26, s2
	s_addc_u32 s11, s27, 0
	v_lshlrev_b32_e32 v213, 2, v212
	global_load_dwordx4 v[150:153], v213, s[10:11]
	global_load_dwordx4 v[154:157], v213, s[10:11] offset:16
	global_load_dwordx4 v[158:161], v213, s[10:11] offset:512
	global_load_dwordx4 v[162:165], v213, s[10:11] offset:528
	v_lshl_add_u32 v149, v149, 10, v212
	v_lshlrev_b32_e32 v149, 2, v149
	s_mov_b64 s[46:47], s[14:15]
	s_mov_b64 s[10:11], s[62:63]
	global_load_dwordx4 v[166:169], v149, s[46:47] nt
	global_load_dwordx4 v[170:173], v149, s[46:47] offset:16 nt
	global_load_dwordx4 v[174:177], v149, s[46:47] offset:512 nt
	global_load_dwordx4 v[178:181], v149, s[46:47] offset:528 nt
	s_add_u32 s46, s46, 0x10000
	s_addc_u32 s47, s47, 0
	global_load_dwordx4 v[182:185], v149, s[46:47] nt
	global_load_dwordx4 v[186:189], v149, s[46:47] offset:16 nt
	global_load_dwordx4 v[190:193], v149, s[46:47] offset:512 nt
	global_load_dwordx4 v[194:197], v149, s[46:47] offset:528 nt
	s_add_u32 s46, s46, 0x10000
	s_addc_u32 s47, s47, 0
	global_load_dwordx4 v[198:201], v149, s[46:47] nt
	global_load_dwordx4 v[202:205], v149, s[46:47] offset:16 nt
	global_load_dwordx4 v[212:215], v149, s[46:47] offset:512 nt
	global_load_dwordx4 v[216:219], v149, s[46:47] offset:528 nt
	s_add_u32 s46, s46, 0x10000
	s_addc_u32 s47, s47, 0
	s_waitcnt vmcnt(10)
	v_pk_fma_f32 v[126:127], v[126:127], v[150:151], v[166:167]
	v_pk_fma_f32 v[128:129], v[128:129], v[152:153], v[168:169]
	v_pk_fma_f32 v[122:123], v[122:123], v[154:155], v[170:171]
	v_pk_fma_f32 v[124:125], v[124:125], v[156:157], v[172:173]
	global_store_dwordx4 v149, v[126:129], s[10:11]
	global_store_dwordx4 v149, v[122:125], s[10:11] offset:16
	global_load_dwordx4 v[166:169], v149, s[46:47] nt
	global_load_dwordx4 v[170:173], v149, s[46:47] offset:16 nt
	s_waitcnt vmcnt(12)
	v_pk_fma_f32 v[118:119], v[118:119], v[158:159], v[174:175]
	v_pk_fma_f32 v[120:121], v[120:121], v[160:161], v[176:177]
	v_pk_fma_f32 v[114:115], v[114:115], v[162:163], v[178:179]
	v_pk_fma_f32 v[116:117], v[116:117], v[164:165], v[180:181]
	global_store_dwordx4 v149, v[118:121], s[10:11] offset:512
	global_store_dwordx4 v149, v[114:117], s[10:11] offset:528
	s_add_u32 s10, s10, 0x10000
	s_addc_u32 s11, s11, 0
	global_load_dwordx4 v[174:177], v149, s[46:47] offset:512 nt
	global_load_dwordx4 v[178:181], v149, s[46:47] offset:528 nt
	s_add_u32 s46, s46, 0x50000
	s_addc_u32 s47, s47, 0
	s_waitcnt vmcnt(14)
	v_pk_fma_f32 v[110:111], v[110:111], v[150:151], v[182:183]
	v_pk_fma_f32 v[112:113], v[112:113], v[152:153], v[184:185]
	v_pk_fma_f32 v[106:107], v[106:107], v[154:155], v[186:187]
	v_pk_fma_f32 v[108:109], v[108:109], v[156:157], v[188:189]
	global_store_dwordx4 v149, v[110:113], s[10:11]
	global_store_dwordx4 v149, v[106:109], s[10:11] offset:16
	global_load_dwordx4 v[182:185], v149, s[46:47] nt
	global_load_dwordx4 v[186:189], v149, s[46:47] offset:16 nt
	s_waitcnt vmcnt(16)
	v_pk_fma_f32 v[102:103], v[102:103], v[158:159], v[190:191]
	v_pk_fma_f32 v[104:105], v[104:105], v[160:161], v[192:193]
	v_pk_fma_f32 v[98:99], v[98:99], v[162:163], v[194:195]
	v_pk_fma_f32 v[100:101], v[100:101], v[164:165], v[196:197]
	global_store_dwordx4 v149, v[102:105], s[10:11] offset:512
	global_store_dwordx4 v149, v[98:101], s[10:11] offset:528
	s_add_u32 s10, s10, 0x10000
	s_addc_u32 s11, s11, 0
	global_load_dwordx4 v[190:193], v149, s[46:47] offset:512 nt
	global_load_dwordx4 v[194:197], v149, s[46:47] offset:528 nt
	s_add_u32 s46, s46, 0x10000
	s_addc_u32 s47, s47, 0
	s_waitcnt vmcnt(18)
	v_pk_fma_f32 v[94:95], v[94:95], v[150:151], v[198:199]
	v_pk_fma_f32 v[96:97], v[96:97], v[152:153], v[200:201]
	v_pk_fma_f32 v[90:91], v[90:91], v[154:155], v[202:203]
	v_pk_fma_f32 v[92:93], v[92:93], v[156:157], v[204:205]
	global_store_dwordx4 v149, v[94:97], s[10:11]
	global_store_dwordx4 v149, v[90:93], s[10:11] offset:16
	global_load_dwordx4 v[198:201], v149, s[46:47] nt
	global_load_dwordx4 v[202:205], v149, s[46:47] offset:16 nt
	s_waitcnt vmcnt(20)
	v_pk_fma_f32 v[86:87], v[86:87], v[158:159], v[212:213]
	v_pk_fma_f32 v[88:89], v[88:89], v[160:161], v[214:215]
	v_pk_fma_f32 v[82:83], v[82:83], v[162:163], v[216:217]
	v_pk_fma_f32 v[84:85], v[84:85], v[164:165], v[218:219]
	global_store_dwordx4 v149, v[86:89], s[10:11] offset:512
	global_store_dwordx4 v149, v[82:85], s[10:11] offset:528
	s_add_u32 s10, s10, 0x10000
	s_addc_u32 s11, s11, 0
	global_load_dwordx4 v[212:215], v149, s[46:47] offset:512 nt
	global_load_dwordx4 v[216:219], v149, s[46:47] offset:528 nt
	s_add_u32 s46, s46, 0x10000
	s_addc_u32 s47, s47, 0
	s_waitcnt vmcnt(20)
; #define GM_WAIT_V(n) asm volatile("s_waitcnt vmcnt(" #n ")" ::: "memory")
; #define GM_BAR __builtin_amdgcn_s_barrier()
; #define GM_SCHED __builtin_amdgcn_sched_barrier(0)
; template <class Epi>
; __device__ __forceinline__ void gemm_phase(const bf16_t* __restrict__ A, const bf16_t* __restrict__ Bt, int M, int N, LAS unsigned char* lds, const Epi& epi, int vcu) {
;     ...
;                     for (int bj = 0; bj < 2; ++bj) { const int m = mp * 2 + mq;
;                         epi(brow + ai * HALF + wr * 64 + m * 16 + fre, (bcol + bj * HALF + wc * 32) >> 5, fqe, acc[ai][bj][m][0], acc[ai][bj][m][1]); }
;                 GM_SCHED;
;             }
;         }
;         if (!have_next) break;
;         brow = nrow; bcol = ncol;
;     }
;     GM_WAIT_V(0);
;     if (wr == 0) GM_BAR;
	v_pk_fma_f32 v[78:79], v[78:79], v[150:151], v[166:167]
	v_pk_fma_f32 v[80:81], v[80:81], v[152:153], v[168:169]
	v_pk_fma_f32 v[74:75], v[74:75], v[154:155], v[170:171]
	v_pk_fma_f32 v[76:77], v[76:77], v[156:157], v[172:173]
	global_store_dwordx4 v149, v[78:81], s[10:11]
	global_store_dwordx4 v149, v[74:77], s[10:11] offset:16
	global_load_dwordx4 v[166:169], v149, s[46:47] nt
	global_load_dwordx4 v[170:173], v149, s[46:47] offset:16 nt
	s_waitcnt vmcnt(20)
	v_pk_fma_f32 v[70:71], v[70:71], v[158:159], v[174:175]
	v_pk_fma_f32 v[72:73], v[72:73], v[160:161], v[176:177]
	v_pk_fma_f32 v[66:67], v[66:67], v[162:163], v[178:179]
	v_pk_fma_f32 v[68:69], v[68:69], v[164:165], v[180:181]
	global_store_dwordx4 v149, v[70:73], s[10:11] offset:512
	global_store_dwordx4 v149, v[66:69], s[10:11] offset:528
	s_add_u32 s10, s10, 0x50000
	s_addc_u32 s11, s11, 0
	global_load_dwordx4 v[174:177], v149, s[46:47] offset:512 nt
	global_load_dwordx4 v[178:181], v149, s[46:47] offset:528 nt
	s_add_u32 s46, s46, 0x10000
	s_addc_u32 s47, s47, 0
	s_waitcnt vmcnt(20)
	v_pk_fma_f32 v[62:63], v[62:63], v[150:151], v[182:183]
	v_pk_fma_f32 v[64:65], v[64:65], v[152:153], v[184:185]
	v_pk_fma_f32 v[58:59], v[58:59], v[154:155], v[186:187]
	v_pk_fma_f32 v[60:61], v[60:61], v[156:157], v[188:189]
	global_store_dwordx4 v149, v[62:65], s[10:11]
	global_store_dwordx4 v149, v[58:61], s[10:11] offset:16
	global_load_dwordx4 v[182:185], v149, s[46:47] nt
	global_load_dwordx4 v[186:189], v149, s[46:47] offset:16 nt
	s_waitcnt vmcnt(20)
	v_pk_fma_f32 v[54:55], v[54:55], v[158:159], v[190:191]
	v_pk_fma_f32 v[56:57], v[56:57], v[160:161], v[192:193]
	v_pk_fma_f32 v[50:51], v[50:51], v[162:163], v[194:195]
	v_pk_fma_f32 v[52:53], v[52:53], v[164:165], v[196:197]
	global_store_dwordx4 v149, v[54:57], s[10:11] offset:512
	global_store_dwordx4 v149, v[50:53], s[10:11] offset:528
	s_add_u32 s10, s10, 0x10000
	s_addc_u32 s11, s11, 0
	global_load_dwordx4 v[190:193], v149, s[46:47] offset:512 nt
	global_load_dwordx4 v[194:197], v149, s[46:47] offset:528 nt
	s_waitcnt vmcnt(20)
	v_pk_fma_f32 v[46:47], v[46:47], v[150:151], v[198:199]
	v_pk_fma_f32 v[48:49], v[48:49], v[152:153], v[200:201]
	v_pk_fma_f32 v[42:43], v[42:43], v[154:155], v[202:203]
	v_pk_fma_f32 v[44:45], v[44:45], v[156:157], v[204:205]
	global_store_dwordx4 v149, v[46:49], s[10:11]
	global_store_dwordx4 v149, v[42:45], s[10:11] offset:16
	s_waitcnt vmcnt(18)
	v_pk_fma_f32 v[38:39], v[38:39], v[158:159], v[212:213]
	v_pk_fma_f32 v[40:41], v[40:41], v[160:161], v[214:215]
	v_pk_fma_f32 v[34:35], v[34:35], v[162:163], v[216:217]
	v_pk_fma_f32 v[36:37], v[36:37], v[164:165], v[218:219]
	global_store_dwordx4 v149, v[38:41], s[10:11] offset:512
	global_store_dwordx4 v149, v[34:37], s[10:11] offset:528
	s_add_u32 s10, s10, 0x10000
	s_addc_u32 s11, s11, 0
	s_waitcnt vmcnt(16)
	v_pk_fma_f32 v[30:31], v[30:31], v[150:151], v[166:167]
	v_pk_fma_f32 v[32:33], v[32:33], v[152:153], v[168:169]
	v_pk_fma_f32 v[26:27], v[26:27], v[154:155], v[170:171]
	v_pk_fma_f32 v[28:29], v[28:29], v[156:157], v[172:173]
	global_store_dwordx4 v149, v[30:33], s[10:11]
	global_store_dwordx4 v149, v[26:29], s[10:11] offset:16
	s_waitcnt vmcnt(14)
	v_pk_fma_f32 v[22:23], v[22:23], v[158:159], v[174:175]
	v_pk_fma_f32 v[24:25], v[24:25], v[160:161], v[176:177]
	v_pk_fma_f32 v[18:19], v[18:19], v[162:163], v[178:179]
	v_pk_fma_f32 v[20:21], v[20:21], v[164:165], v[180:181]
	global_store_dwordx4 v149, v[22:25], s[10:11] offset:512
	global_store_dwordx4 v149, v[18:21], s[10:11] offset:528
	s_add_u32 s10, s10, 0x10000
	s_addc_u32 s11, s11, 0
	s_waitcnt vmcnt(12)
	v_pk_fma_f32 v[14:15], v[14:15], v[150:151], v[182:183]
	v_pk_fma_f32 v[16:17], v[16:17], v[152:153], v[184:185]
	v_pk_fma_f32 v[10:11], v[10:11], v[154:155], v[186:187]
	v_pk_fma_f32 v[12:13], v[12:13], v[156:157], v[188:189]
	global_store_dwordx4 v149, v[14:17], s[10:11]
	global_store_dwordx4 v149, v[10:13], s[10:11] offset:16
	s_waitcnt vmcnt(10)
	v_pk_fma_f32 v[6:7], v[6:7], v[158:159], v[190:191]
	v_pk_fma_f32 v[8:9], v[8:9], v[160:161], v[192:193]
	v_pk_fma_f32 v[2:3], v[2:3], v[162:163], v[194:195]
	v_pk_fma_f32 v[4:5], v[4:5], v[164:165], v[196:197]
	global_store_dwordx4 v149, v[6:9], s[10:11] offset:512
	global_store_dwordx4 v149, v[2:5], s[10:11] offset:528
	v_readlane_b32 s58, v255, 16
	s_and_b64 vcc, exec, s[40:41]
	s_mov_b32 s42, s29
	s_mov_b32 s44, s28
	v_readlane_b32 s59, v255, 17
	v_readlane_b32 s64, v255, 18
	s_mov_b32 s65, 0xf800000
	s_cbranch_vccz .LBB0_332
	s_waitcnt vmcnt(0)
	s_cmpk_gt_u32 s21, 0xff
	s_cbranch_scc1 .LBB0_343
	s_barrier
